# v24 plus compressed-branch loop V fragments read with ds_read_b64 pairs
# speedup vs baseline: 1.0087x; 1.0036x over previous
; #define LAS __attribute__((address_space(3)))
; #define MFMA32(a, b, c) __builtin_amdgcn_mfma_f32_32x32x16_bf16((a), (b), (c), 0, 0, 0)
; DI int crow(int r, int hi) { return (r & 3) + 8 * (r >> 2) + 4 * hi; }
; DI int ccol(int r) { return (r & 3) + 8 * (r >> 2); }
; DI void tile_scores(f32x16& x0, f32x16& x1, const LAS unsigned char* buf, const bf16x8 (&qf)[4], float sk, float aref, int p0, bool laneok, bool needmask, int lo, int hip, int r32, int hi) {
;     KFrag K0, K1; lds_k(K0, buf, 0, r32, hi); lds_k(K1, buf, 1, r32, hi);
;     const float B = laneok ? fmaf(sk, (float)(p0 + 4 * hi), -aref) : -1e30f;
;     const float B1 = B + 32.f * sk;
; #pragma unroll
;     for (int r = 0; r < 16; ++r) { x0[r] = fmaf(sk, (float)ccol(r), B); x1[r] = fmaf(sk, (float)ccol(r), B1); }
; #pragma unroll
;     for (int d0 = 0; d0 < 4; ++d0) { x0 = MFMA32(K0.k[d0], qf[d0], x0); x1 = MFMA32(K1.k[d0], qf[d0], x1); }
;     if (needmask) {
; #pragma unroll
;         for (int r = 0; r < 16; ++r) { const int pos = p0 + crow(r, hi); if (pos < lo || pos > hip) x0[r] = -1e30f; if (pos + 32 < lo || pos + 32 > hip) x1[r] = -1e30f; }
;     }
; }
; DI void nsa_unit(const bf16* PR, const bf16* VT, const bf16* kcb, const bf16* vctb, bf16* Y, LAS unsigned char* lds, int b, int g, int jt) {
;     ...
;             if (64 * i <= nhi_w) {
;                 VFrag V0, V1; lds_v(V0, cbuf, 0, r32, hi); lds_v(V1, cbuf, 1, r32, hi);
;                 f32x16 x0, x1; tile_scores(x0, x1, cbuf, qf, sk, ab + f.mref, 64 * i, true, 64 * i + 63 > nqmin, -(1 << 30), nq, r32, hi);
.LBB0_912:
	s_add_i32 s0, s40, 64
	s_cmp_gt_i32 s0, s48
	s_cbranch_scc1 .LBB0_929
	v_add_u32_e32 v1, s40, v240
	v_add_u32_e32 v14, 64, v1
	v_cvt_f32_u32_e32 v48, v14
	v_add_f32_e32 v15, v121, v131
	ds_read_b128 v[2:5], v130
	ds_read_b128 v[6:9], v130 offset:32
	ds_read_b128 v[10:13], v130 offset:4608
	ds_read_b128 v[88:91], v130 offset:4640
	s_add_i32 s0, s40, 0x7f
	v_fma_f32 v62, v112, v48, -v15
	v_add_f32_e32 v78, v124, v62
	v_fma_f32 v48, 0, v112, v62
	v_add_f32_e32 v49, v112, v62
	v_pk_fma_f32 v[50:51], v[112:113], s[82:83], v[62:63] op_sel_hi:[1,1,0]
	v_pk_fma_f32 v[52:53], v[112:113], s[84:85], v[62:63] op_sel_hi:[1,1,0]
	v_pk_fma_f32 v[54:55], v[112:113], s[86:87], v[62:63] op_sel_hi:[1,1,0]
	v_pk_fma_f32 v[56:57], v[112:113], s[80:81], v[62:63] op_sel_hi:[1,1,0]
	v_pk_fma_f32 v[58:59], v[112:113], s[88:89], v[62:63] op_sel_hi:[1,1,0]
	v_pk_fma_f32 v[60:61], v[112:113], s[90:91], v[62:63] op_sel_hi:[1,1,0]
	v_pk_fma_f32 v[62:63], v[112:113], s[92:93], v[62:63] op_sel_hi:[1,1,0]
	v_fma_f32 v64, 0, v112, v78
	v_add_f32_e32 v65, v112, v78
	s_waitcnt lgkmcnt(3)
	v_mfma_f32_32x32x16_bf16 v[48:63], v[2:5], v[144:147], v[48:63]
	v_fma_f32 v66, v112, s82, v78
	v_fma_f32 v67, v113, s83, v78
	v_fma_f32 v68, v112, s84, v78
	v_fma_f32 v69, v113, s85, v78
	v_fma_f32 v70, v112, s86, v78
	v_fma_f32 v71, v113, s87, v78
	v_pk_fma_f32 v[72:73], v[112:113], s[80:81], v[78:79] op_sel_hi:[1,1,0]
	v_pk_fma_f32 v[74:75], v[112:113], s[88:89], v[78:79] op_sel_hi:[1,1,0]
	v_pk_fma_f32 v[76:77], v[112:113], s[90:91], v[78:79] op_sel_hi:[1,1,0]
	v_pk_fma_f32 v[78:79], v[112:113], s[92:93], v[78:79] op_sel_hi:[1,1,0]
	s_waitcnt lgkmcnt(2)
	v_mfma_f32_32x32x16_bf16 v[48:63], v[6:9], v[148:151], v[48:63]
	ds_read_b128 v[2:5], v130 offset:64
	ds_read_b128 v[6:9], v130 offset:96
	s_cmp_le_i32 s0, s49
	s_waitcnt lgkmcnt(3)
	v_mfma_f32_32x32x16_bf16 v[64:79], v[10:13], v[144:147], v[64:79]
	s_waitcnt lgkmcnt(2)
	v_mfma_f32_32x32x16_bf16 v[64:79], v[88:91], v[148:151], v[64:79]
	s_waitcnt lgkmcnt(1)
	v_mfma_f32_32x32x16_bf16 v[48:63], v[2:5], v[152:155], v[48:63]
	ds_read_b128 v[2:5], v130 offset:4672
	ds_read_b128 v[132:135], v130 offset:4704
	ds_read_b64 v[104:105], v128
	ds_read_b64 v[106:107], v128 offset:16
	ds_read_b64 v[96:97], v128 offset:32
	ds_read_b64 v[98:99], v128 offset:48
	s_waitcnt lgkmcnt(5)
	v_mfma_f32_32x32x16_bf16 v[64:79], v[2:5], v[152:155], v[64:79]
	v_add_u32_e32 v2, 0x1000, v128
	ds_read_b64 v[100:101], v2 offset:256
	ds_read_b64 v[102:103], v2 offset:272
	ds_read_b64 v[92:93], v2 offset:288
	ds_read_b64 v[94:95], v2 offset:304
	v_add_u32_e32 v2, 0x1000, v129
	v_mfma_f32_32x32x16_bf16 v[48:63], v[6:9], v[156:159], v[48:63]
	ds_read_b64 v[88:89], v129
	ds_read_b64 v[90:91], v129 offset:16
	ds_read_b64 v[6:7], v129 offset:32
	ds_read_b64 v[8:9], v129 offset:48
	ds_read_b64 v[10:11], v2 offset:256
	ds_read_b64 v[12:13], v2 offset:272
	ds_read_b64 v[4:5], v2 offset:304
	ds_read_b64 v[2:3], v2 offset:288
	s_waitcnt lgkmcnt(15)
	v_mfma_f32_32x32x16_bf16 v[64:79], v[132:135], v[156:159], v[64:79]
	s_cbranch_scc1 .LBB0_917
	v_add_u32_e32 v15, 0x60, v1
	v_cmp_le_i32_e64 s[6:7], v15, v120
	v_cmp_le_i32_e32 vcc, v14, v120
	s_nop 7
	v_cndmask_b32_e64 v64, v222, v64, s[6:7]
	v_cmp_lt_i32_e64 s[6:7], v14, v120
	v_add_u32_e32 v14, 0x61, v1
	v_cmp_le_i32_e64 s[8:9], v14, v120
	v_add_u32_e32 v14, 0x42, v1
	s_nop 0
	v_cndmask_b32_e64 v65, v222, v65, s[8:9]
	v_cmp_le_i32_e64 s[8:9], v14, v120
	v_add_u32_e32 v14, 0x62, v1
	v_cmp_le_i32_e64 s[10:11], v14, v120
	v_add_u32_e32 v14, 0x43, v1
	s_nop 0
	v_cndmask_b32_e64 v66, v222, v66, s[10:11]
	v_cmp_le_i32_e64 s[10:11], v14, v120
	v_add_u32_e32 v14, 0x63, v1
	v_cmp_le_i32_e64 s[12:13], v14, v120
	v_add_u32_e32 v14, 0x48, v1
	s_nop 0
	v_cndmask_b32_e64 v67, v222, v67, s[12:13]
	v_cmp_le_i32_e64 s[12:13], v14, v120
	v_add_u32_e32 v14, 0x68, v1
	v_cmp_le_i32_e64 s[14:15], v14, v120
	v_add_u32_e32 v14, 0x49, v1
	s_nop 0
	v_cndmask_b32_e64 v68, v222, v68, s[14:15]
	v_cmp_le_i32_e64 s[14:15], v14, v120
	v_add_u32_e32 v14, 0x69, v1
	v_cmp_le_i32_e64 s[16:17], v14, v120
	v_add_u32_e32 v14, 0x4a, v1
	s_nop 0
	v_cndmask_b32_e64 v69, v222, v69, s[16:17]
	v_cmp_le_i32_e64 s[16:17], v14, v120
	v_add_u32_e32 v14, 0x6a, v1
	v_cmp_le_i32_e64 s[18:19], v14, v120
	v_add_u32_e32 v14, 0x4b, v1
	s_nop 0
	v_cndmask_b32_e64 v70, v222, v70, s[18:19]
	v_cmp_le_i32_e64 s[18:19], v14, v120
	v_add_u32_e32 v14, 0x6b, v1
	v_cmp_le_i32_e64 s[20:21], v14, v120
	v_add_u32_e32 v14, 0x50, v1
	s_nop 0
	v_cndmask_b32_e64 v71, v222, v71, s[20:21]
	v_cmp_le_i32_e64 s[20:21], v14, v120
	v_add_u32_e32 v14, 0x70, v1
	v_cmp_le_i32_e64 s[22:23], v14, v120
	v_add_u32_e32 v14, 0x51, v1
	s_nop 0
	v_cndmask_b32_e64 v72, v222, v72, s[22:23]
	v_cmp_le_i32_e64 s[22:23], v14, v120
	v_add_u32_e32 v14, 0x71, v1
	v_cmp_le_i32_e64 s[24:25], v14, v120
	v_add_u32_e32 v14, 0x52, v1
	s_nop 0
	v_cndmask_b32_e64 v73, v222, v73, s[24:25]
	v_cmp_le_i32_e64 s[24:25], v14, v120
	v_add_u32_e32 v14, 0x72, v1
	v_cmp_le_i32_e64 s[26:27], v14, v120
	v_add_u32_e32 v14, 0x53, v1
	s_nop 0
	v_cndmask_b32_e64 v74, v222, v74, s[26:27]
	v_cmp_le_i32_e64 s[26:27], v14, v120
	v_add_u32_e32 v14, 0x73, v1
	v_cmp_le_i32_e64 s[28:29], v14, v120
	v_add_u32_e32 v14, 0x58, v1
	s_nop 0
	v_cndmask_b32_e64 v75, v222, v75, s[28:29]
	v_cmp_le_i32_e64 s[28:29], v14, v120
	v_add_u32_e32 v14, 0x78, v1
	v_cmp_le_i32_e64 s[30:31], v14, v120
	v_add_u32_e32 v14, 0x59, v1
	s_nop 0
	v_cndmask_b32_e64 v76, v222, v76, s[30:31]
	v_cmp_le_i32_e64 s[30:31], v14, v120
	v_add_u32_e32 v14, 0x79, v1
	v_cmp_le_i32_e64 s[34:35], v14, v120
	v_add_u32_e32 v14, 0x5a, v1
	s_nop 0
	v_cndmask_b32_e64 v77, v222, v77, s[34:35]
	v_cmp_le_i32_e64 s[34:35], v14, v120
	v_add_u32_e32 v14, 0x7a, v1
	v_cmp_le_i32_e64 s[36:37], v14, v120
	v_add_u32_e32 v14, 0x5b, v1
	v_add_u32_e32 v1, 0x7b, v1
	v_cndmask_b32_e64 v78, v222, v78, s[36:37]
	v_cmp_le_i32_e64 s[36:37], v14, v120
	v_cmp_gt_i32_e64 s[38:39], v1, v120
	s_and_saveexec_b64 s[4:5], s[38:39]
	v_mov_b32_e32 v79, s75
	s_or_b64 exec, exec, s[4:5]
	v_cndmask_b32_e64 v49, v222, v49, s[6:7]
	v_cndmask_b32_e32 v48, v222, v48, vcc
	v_cndmask_b32_e64 v50, v222, v50, s[8:9]
	v_cndmask_b32_e64 v51, v222, v51, s[10:11]
	v_cndmask_b32_e64 v52, v222, v52, s[12:13]
	v_cndmask_b32_e64 v53, v222, v53, s[14:15]
	v_cndmask_b32_e64 v54, v222, v54, s[16:17]
	v_cndmask_b32_e64 v55, v222, v55, s[18:19]
	v_cndmask_b32_e64 v56, v222, v56, s[20:21]
	v_cndmask_b32_e64 v57, v222, v57, s[22:23]
	v_cndmask_b32_e64 v58, v222, v58, s[24:25]
	v_cndmask_b32_e64 v59, v222, v59, s[26:27]
	v_cndmask_b32_e64 v60, v222, v60, s[28:29]
	v_cndmask_b32_e64 v61, v222, v61, s[30:31]
	v_cndmask_b32_e64 v62, v222, v62, s[34:35]
	v_cndmask_b32_e64 v63, v222, v63, s[36:37]
